# cache-policy: nt hint removed from the diff_final and norm_rows loads (their data was just written on the same XCD)
# speedup vs baseline: 1.0165x; 1.0165x over previous
; __device__ __forceinline__ unsigned pk2(float lo, float hi) { return pg8::cvt_pk_bf16(lo, hi); }
; __device__ __forceinline__ void diff_final(const bfu* D0, const bfu* D1, float lam, const float* sg, float omli, bfu* CAT, int gw, int NGW, int lane) {
;     const int half = lane >> 5, l32 = lane & 31;
;     for (int it = gw * 2 + half; it < M * 6; it += NGW * 2) { const int row = it / 6, h = it - row * 6;
;         const v2u a_ = __builtin_nontemporal_load((const v2u*)(D0 + (size_t)row * 768 + h * 128 + l32 * 4)), b_ = __builtin_nontemporal_load((const v2u*)(D1 + (size_t)row * 768 + h * 128 + l32 * 4));
;         const f32x4 v = (f32x4){bflo(a_.x), bfhi(a_.x), bflo(a_.y), bfhi(a_.y)} - (f32x4){bflo(b_.x), bfhi(b_.x), bflo(b_.y), bfhi(b_.y)} * lam; float s = (v.x * v.x + v.y * v.y) + (v.z * v.z + v.w * v.w);
; #pragma unroll
;         for (int o = 1; o < 32; o <<= 1) s += __shfl_xor(s, o);
;         const float r = omli / sqrtf(s * (1.f / 128.f) + EPS); const f32x4 g4 = *(const f32x4*)(sg + h * 128 + l32 * 4);
;         v2u w; w.x = pk2(v.x * r * g4.x, v.y * r * g4.y); w.y = pk2(v.z * r * g4.z, v.w * r * g4.w); *(v2u*)(CAT + (size_t)row * DM + 768 + h * 128 + l32 * 4) = w; }
.LBB0_501:
	s_mov_b32 s22, 0x2aaaaaab
	v_mul_hi_i32 v16, v10, s22
	v_lshrrev_b32_e32 v17, 31, v16
	v_mov_b64_e32 v[12:13], s[40:41]
	v_add_u32_e32 v16, v16, v17
	v_mad_i64_i32 v[12:13], s[22:23], v16, s66, v[12:13]
	s_movk_i32 s22, 0xfd00
	s_nop 0
	v_mad_u64_u32 v[18:19], s[22:23], v16, s22, v[4:5]
	v_ashrrev_i32_e32 v19, 31, v18
	v_mov_b64_e32 v[14:15], s[44:45]
	v_lshlrev_b64 v[20:21], 1, v[18:19]
	v_mad_i64_i32 v[14:15], s[22:23], v16, s66, v[14:15]
	v_lshl_add_u64 v[12:13], v[12:13], 0, v[20:21]
	v_lshl_add_u64 v[14:15], v[14:15], 0, v[20:21]
	v_lshl_add_u64 v[12:13], v[12:13], 0, v[0:1]
	v_lshl_add_u64 v[14:15], v[14:15], 0, v[0:1]
	global_load_dwordx2 v[22:23], v[12:13], off
	global_load_dwordx2 v[24:25], v[14:15], off
	v_ashrrev_i32_e32 v17, 31, v16
	v_lshlrev_b64 v[12:13], 12, v[16:17]
	v_lshl_add_u64 v[14:15], v[18:19], 2, v[2:3]
	v_lshl_add_u64 v[16:17], s[34:35], 0, v[12:13]
	global_load_dwordx4 v[12:15], v[14:15], off
	s_xor_b32 s47, s20, 0x80000000
	v_lshl_add_u64 v[16:17], v[16:17], 0, v[20:21]
	v_add_u32_e32 v10, 0x40, v10
	s_and_b32 s22, s2, 7
	s_lshl_b32 s22, s22, 3
	s_bfe_u32 s23, s2, 0x30003
	s_add_i32 s22, s22, s23
	s_mulk_i32 s22, 0x600
	s_addk_i32 s22, 0x5ff
	v_cmp_lt_i32_e32 vcc, s22, v10
	s_or_b64 s[36:37], vcc, s[36:37]
	v_lshl_add_u64 v[16:17], v[16:17], 0, v[0:1]
	v_add_u32_e32 v4, 0x2000, v4
	s_waitcnt vmcnt(2)
	v_lshlrev_b32_e32 v18, 16, v22
	v_and_b32_e32 v19, 0xffff0000, v22
	v_lshlrev_b32_e32 v20, 16, v23
	v_and_b32_e32 v21, 0xffff0000, v23
	s_waitcnt vmcnt(1)
	v_lshlrev_b32_e32 v22, 16, v24
	v_and_b32_e32 v23, 0xffff0000, v24
	v_lshlrev_b32_e32 v24, 16, v25
	v_and_b32_e32 v25, 0xffff0000, v25
	v_pk_fma_f32 v[18:19], s[26:27], v[22:23], v[18:19] neg_lo:[1,0,0] neg_hi:[1,0,0]
	v_pk_fma_f32 v[20:21], s[46:47], v[24:25], v[20:21]
	v_pk_mul_f32 v[24:25], v[18:19], v[18:19]
	v_pk_mul_f32 v[22:23], v[20:21], v[20:21]
	s_nop 0
	v_pk_mov_b32 v[26:27], v[24:25], v[22:23] op_sel:[1,0]
	v_mov_b32_e32 v25, v23
	v_pk_add_f32 v[22:23], v[26:27], v[24:25]
	s_nop 0
	v_add_f32_e32 v22, v22, v23
	s_waitcnt lgkmcnt(0)
	s_nop 1
	v_add_f32_dpp v22, v22, v22 quad_perm:[1,0,3,2] row_mask:0xf bank_mask:0xf
	s_nop 1
	v_add_f32_dpp v22, v22, v22 quad_perm:[2,3,0,1] row_mask:0xf bank_mask:0xf
	s_nop 1
	v_add_f32_dpp v22, v22, v22 row_half_mirror row_mask:0xf bank_mask:0xf
	s_nop 1
	v_add_f32_dpp v22, v22, v22 row_mirror row_mask:0xf bank_mask:0xf
	v_mov_b32_e32 v23, v22
	s_nop 1
	v_permlane16_swap_b32_e32 v22, v23
	v_add_f32_e32 v22, v22, v23
	v_fmamk_f32 v22, v22, 0x3c000000, v236
	v_mul_f32_e32 v23, 0x4f800000, v22
	v_cmp_gt_f32_e32 vcc, s68, v22
	s_nop 1
	v_cndmask_b32_e32 v22, v22, v23, vcc
	v_sqrt_f32_e32 v23, v22
	s_nop 0
	v_add_u32_e32 v24, -1, v23
	v_add_u32_e32 v25, 1, v23
	v_fma_f32 v26, -v24, v23, v22
	v_fma_f32 v27, -v25, v23, v22
	v_cmp_ge_f32_e64 s[38:39], 0, v26
	s_nop 1
	v_cndmask_b32_e64 v23, v23, v24, s[38:39]
	v_cmp_lt_f32_e64 s[38:39], 0, v27
	s_nop 1
	v_cndmask_b32_e64 v23, v23, v25, s[38:39]
	v_mul_f32_e32 v24, 0x37800000, v23
	v_cndmask_b32_e32 v23, v23, v24, vcc
	v_cmp_class_f32_e32 vcc, v22, v234
	s_nop 1
	v_cndmask_b32_e32 v22, v23, v22, vcc
	v_div_scale_f32 v23, s[22:23], v22, v22, v11
	v_rcp_f32_e32 v25, v23
	v_div_scale_f32 v24, vcc, v11, v22, v11
	v_fma_f32 v26, -v23, v25, 1.0
	v_fmac_f32_e32 v25, v26, v25
	v_mul_f32_e32 v26, v24, v25
	v_fma_f32 v27, -v23, v26, v24
	v_fmac_f32_e32 v26, v27, v25
	v_fma_f32 v23, -v23, v26, v24
	v_div_fmas_f32 v23, v23, v25, v26
	v_div_fixup_f32 v22, v23, v22, v11
	v_pk_mul_f32 v[18:19], v[18:19], v[22:23] op_sel_hi:[1,0]
	v_pk_mul_f32 v[20:21], v[20:21], v[22:23] op_sel_hi:[1,0]
	v_add_co_u32_e32 v16, vcc, 0x29600000, v16
	s_waitcnt vmcnt(0)
	v_pk_mul_f32 v[12:13], v[12:13], v[18:19]
	v_pk_mul_f32 v[14:15], v[14:15], v[20:21]
	v_addc_co_u32_e32 v17, vcc, 0, v17, vcc
	v_cvt_pk_bf16_f32 v12, v12, v13
	v_cvt_pk_bf16_f32 v13, v14, v15
	global_store_dwordx2 v[16:17], v[12:13], off offset:1536
	s_andn2_b64 exec, exec, s[36:37]
	s_cbranch_execnz .LBB0_501

; template <bool FINAL, bool DUMMY = false> __device__ __forceinline__ void norm_rows(const bfu* F, bfu* XB, const float* g1, float* RS, float* xout, int gw, int NGW, int lane, bfu* dummy = nullptr) {
;     int m = gw; if (m >= M) return;
;     v4u fw[4], xw[4];
; #pragma unroll
;     for (int j = 0; j < 4; ++j) { fw[j] = __builtin_nontemporal_load((const v4u*)(F + (size_t)m * DM) + lane + 64 * j); xw[j] = ((const v4u*)(XB + (size_t)m * DM) + lane)[64 * j]; }
;     for (; m < M; m += NGW) {
;         f32x4 f[8], x[8]; float s = 0.f;
; #pragma unroll
;         for (int j = 0; j < 4; ++j) {
;             f[2 * j] = (f32x4){bflo(fw[j].x), bfhi(fw[j].x), bflo(fw[j].y), bfhi(fw[j].y)}; f[2 * j + 1] = (f32x4){bflo(fw[j].z), bfhi(fw[j].z), bflo(fw[j].w), bfhi(fw[j].w)};
;             x[2 * j] = (f32x4){bflo(xw[j].x), bfhi(xw[j].x), bflo(xw[j].y), bfhi(xw[j].y)}; x[2 * j + 1] = (f32x4){bflo(xw[j].z), bfhi(xw[j].z), bflo(xw[j].w), bfhi(xw[j].w)}; }
;         const int mn = m + NGW;
;         if (mn < M) {
; #pragma unroll
;             for (int j = 0; j < 4; ++j) { fw[j] = __builtin_nontemporal_load((const v4u*)(F + (size_t)mn * DM) + lane + 64 * j); xw[j] = ((const v4u*)(XB + (size_t)mn * DM) + lane)[64 * j]; }
;         }
; #pragma unroll
;         for (int k = 0; k < 8; ++k) s += (f[k].x * f[k].x + f[k].y * f[k].y) + (f[k].z * f[k].z + f[k].w * f[k].w);
;         const float rstd1 = 1.f / sqrtf(wave_sum(s) * (1.f / DM) + EPS);
;         float s2 = 0.f;
; #pragma unroll
;         for (int k = 0; k < 8; ++k) { const f32x4 gg = ((const f32x4*)g1)[2 * lane + 128 * (k >> 1) + (k & 1)]; x[k] = x[k] + f[k] * rstd1 * gg; s2 += (x[k].x * x[k].x + x[k].y * x[k].y) + (x[k].z * x[k].z + x[k].w * x[k].w); }
.LBB0_632:
	s_cmp_le_i32 s58, s20
	s_cselect_b64 s[4:5], -1, 0
	s_and_b64 s[22:23], s[4:5], s[26:27]
	s_andn2_b64 vcc, exec, s[22:23]
	s_cbranch_vccnz .LBB0_640
	v_mov_b32_e32 v0, v232
	s_mov_b32 s42, 21
	v_readfirstlane_b32 s20, v0
	s_ashr_i32 s22, s20, 6
	s_and_b32 s20, s2, 7
	s_lshl_b32 s20, s20, 11
	s_bfe_u32 s27, s2, 0x30003
	s_lshl_b32 s27, s27, 8
	s_add_i32 s20, s20, s27
	s_lshr_b32 s27, s2, 6
	s_lshl_b32 s27, s27, 3
	s_add_i32 s20, s20, s27
	s_add_i32 s26, s22, s20
	s_mov_b32 s40, 21
	s_mov_b32 s36, 14
	s_mov_b32 s34, 21
	s_cmpk_gt_i32 s26, 0x3fff
	s_cbranch_scc1 .LBB0_640
	s_ashr_i32 s43, s42, 31
	s_lshl_b64 s[42:43], s[42:43], 3
	s_add_u32 s42, s0, s42
	s_addc_u32 s43, s1, s43
	s_ashr_i32 s41, s40, 31
	s_lshl_b64 s[40:41], s[40:41], 3
	s_add_u32 s40, s0, s40
	s_addc_u32 s41, s1, s41
	s_ashr_i32 s37, s36, 31
	s_lshl_b64 s[36:37], s[36:37], 3
	s_add_u32 s36, s0, s36
	s_addc_u32 s37, s1, s37
	s_ashr_i32 s35, s34, 31
	s_lshl_b64 s[34:35], s[34:35], 3
	s_add_u32 s44, s0, s34
	s_addc_u32 s45, s1, s35
	s_load_dwordx2 s[34:35], s[42:43], 0x0
	s_nop 0
	s_load_dwordx2 s[36:37], s[36:37], 0x0
	s_nop 0
	s_load_dwordx2 s[44:45], s[44:45], 0x0
	s_nop 0
	s_load_dwordx2 s[42:43], s[40:41], 0x0
	v_readlane_b32 s20, v255, 30
	s_lshl_b32 s20, s20, 11
	s_lshl_b64 s[40:41], s[20:21], 2
	s_waitcnt lgkmcnt(0)
	s_add_u32 s46, s36, s40
	s_addc_u32 s47, s37, s41
	s_ashr_i32 s27, s26, 31
	s_lshl_b64 s[40:41], s[26:27], 12
	v_and_b32_e32 v10, 63, v0
	s_add_u32 s36, s42, s40
	v_lshlrev_b32_e32 v0, 4, v10
	s_addc_u32 s37, s43, s41
	v_lshl_add_u64 v[2:3], s[36:37], 0, v[0:1]
	s_mov_b64 s[48:49], 0x18e00000
	s_add_u32 s40, s34, s40
	s_mov_b32 s20, 0x18e00000
	v_lshl_add_u64 v[4:5], v[2:3], 0, s[48:49]
	s_addc_u32 s41, s35, s41
	v_add_co_u32_e32 v2, vcc, s20, v2
	v_lshl_add_u64 v[6:7], s[40:41], 0, v[0:1]
	s_nop 0
	v_addc_co_u32_e32 v3, vcc, 0, v3, vcc
	s_mov_b32 s20, 0x2d600000
	global_load_dwordx4 v[34:37], v[4:5], off offset:3072
	global_load_dwordx4 v[42:45], v[4:5], off offset:2048
	global_load_dwordx4 v[50:53], v[4:5], off offset:1024
	global_load_dwordx4 v[54:57], v[2:3], off
	v_add_co_u32_e32 v2, vcc, s20, v6
	s_mov_b64 s[40:41], 0x2d600000
	s_nop 0
	v_addc_co_u32_e32 v3, vcc, 0, v7, vcc
	v_lshl_add_u64 v[8:9], v[6:7], 0, s[40:41]
	global_load_dwordx4 v[62:65], v[2:3], off
	global_load_dwordx4 v[58:61], v[8:9], off offset:1024
	global_load_dwordx4 v[46:49], v[8:9], off offset:2048
	global_load_dwordx4 v[38:41], v[8:9], off offset:3072
	v_and_b32_e32 v2, 64, v240
	v_mov_b32_e32 v3, v1
	v_add_u32_e32 v11, 64, v2
	v_lshlrev_b32_e32 v2, 5, v10
	v_lshl_add_u64 v[66:67], s[46:47], 0, v[2:3]
	s_mov_b64 s[46:47], 0x1000
	v_lshl_add_u64 v[68:69], v[66:67], 0, s[46:47]
	s_mov_b64 s[46:47], 0x1800
	v_lshl_add_u64 v[70:71], v[66:67], 0, s[46:47]
	global_load_dwordx4 v[128:131], v[66:67], off offset:16
	global_load_dwordx4 v[132:135], v[66:67], off
	global_load_dwordx4 v[136:139], v[66:67], off offset:2064
	global_load_dwordx4 v[140:143], v[66:67], off offset:2048
	global_load_dwordx4 v[144:147], v[68:69], off offset:16
	global_load_dwordx4 v[148:151], v[68:69], off
	global_load_dwordx4 v[152:155], v[70:71], off offset:16
	global_load_dwordx4 v[156:159], v[70:71], off
	s_waitcnt vmcnt(0)
	s_lshl_b64 s[46:47], s[26:27], 2
	v_xor_b32_e32 v4, 1, v240
	s_add_u32 s20, s44, s46
	v_xor_b32_e32 v5, 2, v240
	v_cmp_lt_i32_e32 vcc, v4, v11
	s_addc_u32 s23, s45, s47
	v_xor_b32_e32 v6, 4, v240
	v_cndmask_b32_e32 v4, v240, v4, vcc
	v_cmp_lt_i32_e32 vcc, v5, v11
	s_add_u32 s44, s20, 0x1c0000
	v_xor_b32_e32 v7, 8, v240
	v_cndmask_b32_e32 v5, v240, v5, vcc
	v_cmp_lt_i32_e32 vcc, v6, v11
	s_addc_u32 s45, s23, 0
	s_sub_i32 s20, s26, s22
	s_addk_i32 s20, 0x20
	s_and_b32 s26, s26, 0x7ff
	s_add_i32 s22, s20, s22
	v_xor_b32_e32 v8, 16, v240
	v_cndmask_b32_e32 v6, v240, v6, vcc
	v_cmp_lt_i32_e32 vcc, v7, v11
	s_ashr_i32 s23, s22, 31
	v_xor_b32_e32 v9, 32, v240
	v_cndmask_b32_e32 v7, v240, v7, vcc
	v_cmp_lt_i32_e32 vcc, v8, v11
	s_lshl_b64 s[22:23], s[22:23], 12
	s_add_u32 s46, s34, s22
	v_cndmask_b32_e32 v8, v240, v8, vcc
	v_cmp_lt_i32_e32 vcc, v9, v11
	s_addc_u32 s47, s35, s23
	v_cmp_eq_u32_e64 s[40:41], 0, v10
	v_cndmask_b32_e32 v9, v240, v9, vcc
	v_lshlrev_b32_e32 v116, 2, v4
	v_lshlrev_b32_e32 v117, 2, v5
	v_lshlrev_b32_e32 v118, 2, v6
	v_lshlrev_b32_e32 v119, 2, v7
	v_lshlrev_b32_e32 v120, 2, v8
	v_lshlrev_b32_e32 v121, 2, v9
	s_add_u32 s50, s42, s22
	s_addc_u32 s51, s43, s23
	s_waitcnt vmcnt(0)
	v_mov_b64_e32 v[18:19], v[42:43]
	v_mov_b64_e32 v[10:11], v[50:51]
	v_mov_b64_e32 v[2:3], v[54:55]
	v_mov_b64_e32 v[22:23], v[34:35]
	v_mov_b64_e32 v[4:5], v[56:57]
	v_mov_b64_e32 v[12:13], v[52:53]
	v_mov_b64_e32 v[6:7], v[62:63]
	v_mov_b64_e32 v[14:15], v[58:59]
	v_mov_b64_e32 v[26:27], v[46:47]
	v_mov_b64_e32 v[30:31], v[38:39]
	v_mov_b64_e32 v[20:21], v[44:45]
	v_mov_b64_e32 v[24:25], v[36:37]
	v_mov_b64_e32 v[8:9], v[64:65]
	v_mov_b64_e32 v[16:17], v[60:61]
	v_mov_b64_e32 v[28:29], v[48:49]
	v_mov_b64_e32 v[32:33], v[40:41]
	s_branch .LBB0_636

; template <bool FINAL, bool DUMMY = false> __device__ __forceinline__ void norm_rows(const bfu* F, bfu* XB, const float* g1, float* RS, float* xout, int gw, int NGW, int lane, bfu* dummy = nullptr) {
;     ...
;         const int mn = m + NGW;
;         if (mn < M) {
; #pragma unroll
;             for (int j = 0; j < 4; ++j) { fw[j] = __builtin_nontemporal_load((const v4u*)(F + (size_t)mn * DM) + lane + 64 * j); xw[j] = ((const v4u*)(XB + (size_t)mn * DM) + lane)[64 * j]; }
;         }
.LBB0_636:
	s_add_i32 s26, s26, s54
	s_cmpk_gt_i32 s26, 0x3fff
	s_cselect_b64 s[52:53], -1, 0
	s_and_b64 vcc, exec, s[52:53]
	s_cbranch_vccnz .LBB0_638
	v_lshl_add_u64 v[2:3], s[46:47], 0, v[0:1]
	v_add_co_u32_e32 v18, vcc, 0x2d600000, v2
	v_lshl_add_u64 v[4:5], s[50:51], 0, v[0:1]
	s_nop 0
	v_addc_co_u32_e32 v19, vcc, 0, v3, vcc
	v_add_co_u32_e32 v22, vcc, 0x18e00000, v4
	s_nop 1
	v_addc_co_u32_e32 v23, vcc, 0, v5, vcc
	global_load_dwordx4 v[6:9], v[18:19], off
	global_load_dwordx4 v[14:17], v[18:19], off offset:1024
	global_load_dwordx4 v[2:5], v[22:23], off
	global_load_dwordx4 v[10:13], v[22:23], off offset:1024
	global_load_dwordx4 v[26:29], v[18:19], off offset:2048
	global_load_dwordx4 v[30:33], v[18:19], off offset:3072
	s_nop 0
	global_load_dwordx4 v[18:21], v[22:23], off offset:2048
	s_nop 0
	global_load_dwordx4 v[22:25], v[22:23], off offset:3072

; template <bool FINAL, bool DUMMY = false> __device__ __forceinline__ void norm_rows(const bfu* F, bfu* XB, const float* g1, float* RS, float* xout, int gw, int NGW, int lane, bfu* dummy = nullptr) {
;     int m = gw; if (m >= M) return;
;     v4u fw[4], xw[4];
; #pragma unroll
;     for (int j = 0; j < 4; ++j) { fw[j] = __builtin_nontemporal_load((const v4u*)(F + (size_t)m * DM) + lane + 64 * j); xw[j] = ((const v4u*)(XB + (size_t)m * DM) + lane)[64 * j]; }
;     for (; m < M; m += NGW) {
;         f32x4 f[8], x[8]; float s = 0.f;
; #pragma unroll
;         for (int j = 0; j < 4; ++j) {
;             f[2 * j] = (f32x4){bflo(fw[j].x), bfhi(fw[j].x), bflo(fw[j].y), bfhi(fw[j].y)}; f[2 * j + 1] = (f32x4){bflo(fw[j].z), bfhi(fw[j].z), bflo(fw[j].w), bfhi(fw[j].w)};
;             x[2 * j] = (f32x4){bflo(xw[j].x), bfhi(xw[j].x), bflo(xw[j].y), bfhi(xw[j].y)}; x[2 * j + 1] = (f32x4){bflo(xw[j].z), bfhi(xw[j].z), bflo(xw[j].w), bfhi(xw[j].w)}; }
;         const int mn = m + NGW;
;         if (mn < M) {
; #pragma unroll
;             for (int j = 0; j < 4; ++j) { fw[j] = __builtin_nontemporal_load((const v4u*)(F + (size_t)mn * DM) + lane + 64 * j); xw[j] = ((const v4u*)(XB + (size_t)mn * DM) + lane)[64 * j]; }
;         }
; #pragma unroll
;         for (int k = 0; k < 8; ++k) s += (f[k].x * f[k].x + f[k].y * f[k].y) + (f[k].z * f[k].z + f[k].w * f[k].w);
;         const float rstd1 = 1.f / sqrtf(wave_sum(s) * (1.f / DM) + EPS);
;         float s2 = 0.f;
; #pragma unroll
;         for (int k = 0; k < 8; ++k) { const f32x4 gg = ((const f32x4*)g1)[2 * lane + 128 * (k >> 1) + (k & 1)]; x[k] = x[k] + f[k] * rstd1 * gg; s2 += (x[k].x * x[k].x + x[k].y * x[k].y) + (x[k].z * x[k].z + x[k].w * x[k].w); }
.LBB0_844:
	s_cmp_le_i32 s58, s20
	s_cselect_b64 s[4:5], -1, 0
	s_and_b64 s[22:23], s[4:5], s[26:27]
	s_andn2_b64 vcc, exec, s[22:23]
	s_cbranch_vccnz .LBB0_860
	v_mov_b32_e32 v0, v232
	s_mov_b64 s[34:35], -1
	v_readfirstlane_b32 s20, v0
	s_ashr_i32 s48, s20, 6
	s_and_b32 s20, s2, 7
	s_lshl_b32 s20, s20, 11
	s_bfe_u32 s27, s2, 0x30003
	s_lshl_b32 s27, s27, 8
	s_add_i32 s20, s20, s27
	s_lshr_b32 s27, s2, 6
	s_lshl_b32 s27, s27, 3
	s_add_i32 s20, s20, s27
	s_add_i32 s26, s48, s20
	v_readlane_b32 s20, v255, 30
	s_cmp_eq_u32 s20, 3
	v_and_b32_e32 v116, 63, v0
	s_cbranch_scc1 .LBB0_854
	s_mov_b32 s34, 21
	s_mov_b32 s40, 21
	s_mov_b32 s38, 19
	s_mov_b32 s36, 21
	s_cmpk_gt_i32 s26, 0x3fff
	s_cbranch_scc1 .LBB0_853
	s_ashr_i32 s35, s34, 31
	s_lshl_b64 s[22:23], s[34:35], 3
	s_add_u32 s22, s0, s22
	s_addc_u32 s23, s1, s23
	s_ashr_i32 s41, s40, 31
	s_load_dwordx2 s[34:35], s[22:23], 0x0
	s_lshl_b64 s[22:23], s[40:41], 3
	s_add_u32 s22, s0, s22
	s_addc_u32 s23, s1, s23
	s_ashr_i32 s39, s38, 31
	s_load_dwordx2 s[40:41], s[22:23], 0x0
	s_lshl_b64 s[22:23], s[38:39], 3
	s_add_u32 s22, s0, s22
	s_addc_u32 s23, s1, s23
	s_load_dwordx2 s[22:23], s[22:23], 0x0
	s_ashr_i32 s37, s36, 31
	s_lshl_b64 s[36:37], s[36:37], 3
	s_add_u32 s36, s0, s36
	v_readlane_b32 s20, v255, 30
	s_addc_u32 s37, s1, s37
	s_lshl_b32 s20, s20, 11
	s_load_dwordx2 s[42:43], s[36:37], 0x0
	s_lshl_b64 s[36:37], s[20:21], 2
	s_waitcnt lgkmcnt(0)
	s_add_u32 s44, s22, s36
	s_addc_u32 s45, s23, s37
	s_ashr_i32 s27, s26, 31
	s_lshl_b64 s[22:23], s[26:27], 12
	s_add_u32 s36, s40, s22
	s_addc_u32 s37, s41, s23
	v_lshlrev_b32_e32 v0, 4, v116
	s_add_u32 s22, s34, s22
	v_lshl_add_u64 v[2:3], s[36:37], 0, v[0:1]
	s_mov_b64 s[38:39], 0x18e00000
	s_addc_u32 s23, s35, s23
	s_mov_b32 s20, 0x18e00000
	v_lshl_add_u64 v[4:5], v[2:3], 0, s[38:39]
	v_lshl_add_u64 v[6:7], s[22:23], 0, v[0:1]
	s_mov_b64 s[22:23], 0x2d600000
	v_add_co_u32_e32 v2, vcc, s20, v2
	v_lshl_add_u64 v[8:9], v[6:7], 0, s[22:23]
	s_nop 0
	v_addc_co_u32_e32 v3, vcc, 0, v3, vcc
	s_mov_b32 s20, 0x2d600000
	global_load_dwordx4 v[34:37], v[4:5], off offset:3072
	global_load_dwordx4 v[38:41], v[8:9], off offset:3072
	global_load_dwordx4 v[42:45], v[4:5], off offset:2048
	global_load_dwordx4 v[46:49], v[8:9], off offset:2048
	global_load_dwordx4 v[50:53], v[4:5], off offset:1024
	global_load_dwordx4 v[54:57], v[8:9], off offset:1024
	global_load_dwordx4 v[58:61], v[2:3], off
	v_add_co_u32_e32 v2, vcc, s20, v6
	s_mov_b64 s[22:23], 0x1000
	s_nop 0
	v_addc_co_u32_e32 v3, vcc, 0, v7, vcc
	global_load_dwordx4 v[62:65], v[2:3], off
	v_and_b32_e32 v2, 64, v240
	v_add_u32_e32 v2, 64, v2
	v_xor_b32_e32 v3, 1, v240
	v_cmp_lt_i32_e32 vcc, v3, v2
	v_cmp_eq_u32_e64 s[38:39], 0, v116
	s_waitcnt vmcnt(0)
	v_mov_b64_e32 v[30:31], v[38:39]
	v_cndmask_b32_e32 v3, v240, v3, vcc
	v_lshlrev_b32_e32 v117, 2, v3
	v_xor_b32_e32 v3, 2, v240
	v_cmp_lt_i32_e32 vcc, v3, v2
	v_mov_b64_e32 v[10:11], v[50:51]
	v_mov_b64_e32 v[18:19], v[42:43]
	v_cndmask_b32_e32 v3, v240, v3, vcc
	v_lshlrev_b32_e32 v118, 2, v3
	v_xor_b32_e32 v3, 4, v240
	v_cmp_lt_i32_e32 vcc, v3, v2
	v_mov_b64_e32 v[22:23], v[34:35]
	v_mov_b64_e32 v[6:7], v[62:63]
	v_cndmask_b32_e32 v3, v240, v3, vcc
	v_lshlrev_b32_e32 v119, 2, v3
	v_xor_b32_e32 v3, 8, v240
	v_cmp_lt_i32_e32 vcc, v3, v2
	v_mov_b64_e32 v[14:15], v[54:55]
	v_mov_b64_e32 v[26:27], v[46:47]
	v_cndmask_b32_e32 v3, v240, v3, vcc
	v_lshlrev_b32_e32 v120, 2, v3
	v_xor_b32_e32 v3, 16, v240
	v_cmp_lt_i32_e32 vcc, v3, v2
	v_mov_b64_e32 v[12:13], v[52:53]
	v_mov_b64_e32 v[20:21], v[44:45]
	v_cndmask_b32_e32 v3, v240, v3, vcc
	v_lshlrev_b32_e32 v121, 2, v3
	v_xor_b32_e32 v3, 32, v240
	v_cmp_lt_i32_e32 vcc, v3, v2
	v_mov_b64_e32 v[24:25], v[36:37]
	v_mov_b64_e32 v[8:9], v[64:65]
	v_cndmask_b32_e32 v2, v240, v3, vcc
	v_lshlrev_b32_e32 v122, 2, v2
	v_lshlrev_b32_e32 v2, 5, v116
	v_mov_b32_e32 v3, v1
	v_lshl_add_u64 v[66:67], s[44:45], 0, v[2:3]
	v_lshl_add_u64 v[68:69], v[66:67], 0, s[22:23]
	s_mov_b64 s[22:23], 0x1800
	v_lshl_add_u64 v[70:71], v[66:67], 0, s[22:23]
	global_load_dwordx4 v[128:131], v[66:67], off offset:16
	global_load_dwordx4 v[132:135], v[66:67], off
	global_load_dwordx4 v[136:139], v[66:67], off offset:2064
	global_load_dwordx4 v[140:143], v[66:67], off offset:2048
	global_load_dwordx4 v[144:147], v[68:69], off offset:16
	global_load_dwordx4 v[148:151], v[68:69], off
	global_load_dwordx4 v[152:155], v[70:71], off offset:16
	global_load_dwordx4 v[156:159], v[70:71], off
	s_waitcnt vmcnt(0)
	s_lshl_b64 s[22:23], s[26:27], 2
	s_add_u32 s20, s42, s22
	s_addc_u32 s22, s43, s23
	s_add_u32 s42, s20, 0x1c0000
	s_addc_u32 s43, s22, 0
	s_sub_i32 s20, s26, s48
	s_addk_i32 s20, 0x20
	s_add_i32 s22, s20, s48
	s_ashr_i32 s23, s22, 31
	s_lshl_b64 s[22:23], s[22:23], 12
	s_add_u32 s44, s34, s22
	s_addc_u32 s45, s35, s23
	s_add_u32 s46, s40, s22
	v_mov_b64_e32 v[2:3], v[58:59]
	s_addc_u32 s47, s41, s23
	s_and_b32 s20, s26, 0x7ff
	v_mov_b64_e32 v[4:5], v[60:61]
	v_mov_b64_e32 v[16:17], v[56:57]
	v_mov_b64_e32 v[28:29], v[48:49]
	v_mov_b64_e32 v[32:33], v[40:41]
	s_branch .LBB0_849

; template <bool FINAL, bool DUMMY = false> __device__ __forceinline__ void norm_rows(const bfu* F, bfu* XB, const float* g1, float* RS, float* xout, int gw, int NGW, int lane, bfu* dummy = nullptr) {
;     ...
;         const int mn = m + NGW;
;         if (mn < M) {
; #pragma unroll
;             for (int j = 0; j < 4; ++j) { fw[j] = __builtin_nontemporal_load((const v4u*)(F + (size_t)mn * DM) + lane + 64 * j); xw[j] = ((const v4u*)(XB + (size_t)mn * DM) + lane)[64 * j]; }
;         }
.LBB0_849:
	s_add_i32 s20, s20, s54
	s_cmpk_gt_i32 s20, 0x3fff
	s_cselect_b64 s[50:51], -1, 0
	s_and_b64 vcc, exec, s[50:51]
	s_cbranch_vccnz .LBB0_851
	v_lshl_add_u64 v[2:3], s[44:45], 0, v[0:1]
	v_add_co_u32_e32 v18, vcc, 0x2d600000, v2
	v_lshl_add_u64 v[4:5], s[46:47], 0, v[0:1]
	s_nop 0
	v_addc_co_u32_e32 v19, vcc, 0, v3, vcc
	v_add_co_u32_e32 v22, vcc, 0x18e00000, v4
	s_nop 1
	v_addc_co_u32_e32 v23, vcc, 0, v5, vcc
	global_load_dwordx4 v[6:9], v[18:19], off
	global_load_dwordx4 v[14:17], v[18:19], off offset:1024
	global_load_dwordx4 v[2:5], v[22:23], off
	global_load_dwordx4 v[10:13], v[22:23], off offset:1024
	global_load_dwordx4 v[26:29], v[18:19], off offset:2048
	global_load_dwordx4 v[30:33], v[18:19], off offset:3072
	s_nop 0
	global_load_dwordx4 v[18:21], v[22:23], off offset:2048
	s_nop 0
	global_load_dwordx4 v[22:25], v[22:23], off offset:3072

; template <bool FINAL, bool DUMMY = false> __device__ __forceinline__ void norm_rows(const bfu* F, bfu* XB, const float* g1, float* RS, float* xout, int gw, int NGW, int lane, bfu* dummy = nullptr) {
;     int m = gw; if (m >= M) return;
;     v4u fw[4], xw[4];
; #pragma unroll
;     for (int j = 0; j < 4; ++j) { fw[j] = __builtin_nontemporal_load((const v4u*)(F + (size_t)m * DM) + lane + 64 * j); xw[j] = ((const v4u*)(XB + (size_t)m * DM) + lane)[64 * j]; }
;     for (; m < M; m += NGW) {
;         f32x4 f[8], x[8]; float s = 0.f;
; #pragma unroll
;         for (int j = 0; j < 4; ++j) {
;             f[2 * j] = (f32x4){bflo(fw[j].x), bfhi(fw[j].x), bflo(fw[j].y), bfhi(fw[j].y)}; f[2 * j + 1] = (f32x4){bflo(fw[j].z), bfhi(fw[j].z), bflo(fw[j].w), bfhi(fw[j].w)};
;             x[2 * j] = (f32x4){bflo(xw[j].x), bfhi(xw[j].x), bflo(xw[j].y), bfhi(xw[j].y)}; x[2 * j + 1] = (f32x4){bflo(xw[j].z), bfhi(xw[j].z), bflo(xw[j].w), bfhi(xw[j].w)}; }
;         const int mn = m + NGW;
;         if (mn < M) {
; #pragma unroll
;             for (int j = 0; j < 4; ++j) { fw[j] = __builtin_nontemporal_load((const v4u*)(F + (size_t)mn * DM) + lane + 64 * j); xw[j] = ((const v4u*)(XB + (size_t)mn * DM) + lane)[64 * j]; }
;         }
; #pragma unroll
;         for (int k = 0; k < 8; ++k) s += (f[k].x * f[k].x + f[k].y * f[k].y) + (f[k].z * f[k].z + f[k].w * f[k].w);
;         const float rstd1 = 1.f / sqrtf(wave_sum(s) * (1.f / DM) + EPS);
;         float s2 = 0.f;
; #pragma unroll
;         for (int k = 0; k < 8; ++k) { const f32x4 gg = ((const f32x4*)g1)[2 * lane + 128 * (k >> 1) + (k & 1)]; x[k] = x[k] + f[k] * rstd1 * gg; s2 += (x[k].x * x[k].x + x[k].y * x[k].y) + (x[k].z * x[k].z + x[k].w * x[k].w); }
;         if (FINAL) { f32x4* xo = (f32x4*)(xout + (size_t)m * DM);
; #pragma unroll
;             for (int k = 0; k < 8; ++k) __builtin_nontemporal_store(x[k], xo + 2 * lane + 128 * (k >> 1) + (k & 1));
.LBB0_854:
	s_andn2_b64 vcc, exec, s[34:35]
	s_cbranch_vccnz .LBB0_860
	s_mov_b32 s40, 21
	s_mov_b32 s38, 21
	s_mov_b32 s36, 19
	s_mov_b32 s34, 20
	s_cmpk_gt_i32 s26, 0x3fff
	s_cbranch_scc1 .LBB0_860
	s_ashr_i32 s41, s40, 31
	s_lshl_b64 s[22:23], s[40:41], 3
	s_add_u32 s22, s0, s22
	s_addc_u32 s23, s1, s23
	s_ashr_i32 s39, s38, 31
	s_lshl_b64 s[38:39], s[38:39], 3
	s_add_u32 s38, s0, s38
	s_addc_u32 s39, s1, s39
	s_ashr_i32 s37, s36, 31
	s_lshl_b64 s[36:37], s[36:37], 3
	s_add_u32 s40, s0, s36
	s_addc_u32 s41, s1, s37
	s_ashr_i32 s35, s34, 31
	s_lshl_b64 s[34:35], s[34:35], 3
	s_add_u32 s42, s0, s34
	s_addc_u32 s43, s1, s35
	s_load_dwordx2 s[34:35], s[22:23], 0x0
	s_load_dwordx2 s[36:37], s[38:39], 0x0
	s_nop 0
	s_load_dwordx2 s[22:23], s[40:41], 0x0
	s_load_dwordx2 s[38:39], s[42:43], 0x0
	s_ashr_i32 s27, s26, 31
	s_lshl_b64 s[40:41], s[26:27], 12
	s_waitcnt lgkmcnt(0)
	s_add_u32 s42, s36, s40
	s_addc_u32 s43, s37, s41
	v_lshlrev_b32_e32 v0, 4, v116
	v_lshl_add_u64 v[2:3], s[42:43], 0, v[0:1]
	s_mov_b64 s[42:43], 0x18e00000
	s_add_u32 s40, s34, s40
	s_mov_b32 s20, 0x18e00000
	v_lshl_add_u64 v[4:5], v[2:3], 0, s[42:43]
	s_addc_u32 s41, s35, s41
	v_add_co_u32_e32 v2, vcc, s20, v2
	v_lshl_add_u64 v[6:7], s[40:41], 0, v[0:1]
	s_nop 0
	v_addc_co_u32_e32 v3, vcc, 0, v3, vcc
	s_mov_b32 s20, 0x2d600000
	global_load_dwordx4 v[34:37], v[4:5], off offset:3072
	global_load_dwordx4 v[42:45], v[4:5], off offset:2048
	global_load_dwordx4 v[50:53], v[4:5], off offset:1024
	global_load_dwordx4 v[58:61], v[2:3], off
	v_add_co_u32_e32 v2, vcc, s20, v6
	s_mov_b64 s[40:41], 0x2d600000
	s_nop 0
	v_addc_co_u32_e32 v3, vcc, 0, v7, vcc
	v_lshl_add_u64 v[8:9], v[6:7], 0, s[40:41]
	global_load_dwordx4 v[62:65], v[2:3], off
	global_load_dwordx4 v[54:57], v[8:9], off offset:1024
	global_load_dwordx4 v[46:49], v[8:9], off offset:2048
	global_load_dwordx4 v[38:41], v[8:9], off offset:3072
	v_and_b32_e32 v4, 64, v240
	v_xor_b32_e32 v5, 1, v240
	v_add_u32_e32 v4, 64, v4
	v_xor_b32_e32 v6, 2, v240
	v_cmp_lt_i32_e32 vcc, v5, v4
	v_xor_b32_e32 v7, 4, v240
	v_xor_b32_e32 v8, 8, v240
	v_cndmask_b32_e32 v5, v240, v5, vcc
	v_cmp_lt_i32_e32 vcc, v6, v4
	v_xor_b32_e32 v9, 16, v240
	v_xor_b32_e32 v10, 32, v240
	v_cndmask_b32_e32 v6, v240, v6, vcc
	v_cmp_lt_i32_e32 vcc, v7, v4
	v_lshlrev_b32_e32 v2, 5, v116
	v_mov_b32_e32 v3, v1
	v_cndmask_b32_e32 v7, v240, v7, vcc
	v_cmp_lt_i32_e32 vcc, v8, v4
	v_lshlrev_b32_e32 v91, 2, v5
	s_sub_i32 s20, s26, s48
	s_addk_i32 s20, 0x20
	v_cndmask_b32_e32 v8, v240, v8, vcc
	v_cmp_lt_i32_e32 vcc, v9, v4
	v_lshlrev_b32_e32 v124, 2, v6
	v_lshlrev_b32_e32 v125, 2, v7
	v_cndmask_b32_e32 v9, v240, v9, vcc
	v_cmp_lt_i32_e32 vcc, v10, v4
	v_lshlrev_b32_e32 v126, 2, v8
	v_lshlrev_b32_e32 v127, 2, v9
	v_cndmask_b32_e32 v4, v240, v10, vcc
	v_lshlrev_b32_e32 v128, 2, v4
	v_lshl_add_u64 v[4:5], s[22:23], 0, v[2:3]
	s_mov_b64 s[22:23], 0x6000
	v_lshl_add_u64 v[66:67], v[4:5], 0, s[22:23]
	s_mov_b64 s[22:23], 0x7000
	v_lshl_add_u64 v[68:69], v[4:5], 0, s[22:23]
	s_mov_b64 s[22:23], 0x7800
	v_lshl_add_u64 v[70:71], v[4:5], 0, s[22:23]
	s_lshl_b64 s[22:23], s[26:27], 13
	s_and_b32 s26, s26, 0x7ff
	s_add_u32 s22, s38, s22
	s_addc_u32 s23, s39, s23
	s_add_i32 s38, s20, s48
	v_lshl_add_u64 v[2:3], s[22:23], 0, v[2:3]
	s_ashr_i32 s39, s38, 31
	s_mov_b64 s[22:23], 0x1000
	v_lshl_add_u64 v[72:73], v[2:3], 0, s[22:23]
	s_lshl_b64 s[22:23], s[38:39], 12
	s_add_u32 s36, s36, s22
	s_addc_u32 s37, s37, s23
	s_add_u32 s40, s34, s22
	s_addc_u32 s41, s35, s23
	s_waitcnt vmcnt(0)
	v_mov_b64_e32 v[18:19], v[42:43]
	v_mov_b64_e32 v[10:11], v[50:51]
	v_mov_b64_e32 v[2:3], v[58:59]
	v_mov_b64_e32 v[22:23], v[34:35]
	v_mov_b64_e32 v[4:5], v[60:61]
	v_mov_b64_e32 v[12:13], v[52:53]
	v_mov_b64_e32 v[6:7], v[62:63]
	v_mov_b64_e32 v[14:15], v[54:55]
	v_mov_b64_e32 v[26:27], v[46:47]
	v_mov_b64_e32 v[30:31], v[38:39]
	v_mov_b64_e32 v[20:21], v[44:45]
	v_mov_b64_e32 v[24:25], v[36:37]
	v_mov_b64_e32 v[8:9], v[64:65]
	v_mov_b64_e32 v[16:17], v[56:57]
	v_mov_b64_e32 v[28:29], v[48:49]
	v_mov_b64_e32 v[32:33], v[40:41]
	s_branch .LBB0_858

; template <bool FINAL, bool DUMMY = false> __device__ __forceinline__ void norm_rows(const bfu* F, bfu* XB, const float* g1, float* RS, float* xout, int gw, int NGW, int lane, bfu* dummy = nullptr) {
;     ...
;         const int mn = m + NGW;
;         if (mn < M) {
; #pragma unroll
;             for (int j = 0; j < 4; ++j) { fw[j] = __builtin_nontemporal_load((const v4u*)(F + (size_t)mn * DM) + lane + 64 * j); xw[j] = ((const v4u*)(XB + (size_t)mn * DM) + lane)[64 * j]; }
;         }
.LBB0_858:
	s_add_i32 s26, s26, s54
	s_cmpk_gt_i32 s26, 0x3fff
	s_cselect_b64 s[42:43], -1, 0
	s_and_b64 vcc, exec, s[42:43]
	s_cbranch_vccnz .LBB0_857
	v_lshl_add_u64 v[2:3], s[40:41], 0, v[0:1]
	v_add_co_u32_e32 v18, vcc, 0x2d600000, v2
	v_lshl_add_u64 v[4:5], s[36:37], 0, v[0:1]
	s_nop 0
	v_addc_co_u32_e32 v19, vcc, 0, v3, vcc
	v_add_co_u32_e32 v22, vcc, 0x18e00000, v4
	s_nop 1
	v_addc_co_u32_e32 v23, vcc, 0, v5, vcc
	global_load_dwordx4 v[6:9], v[18:19], off
	global_load_dwordx4 v[14:17], v[18:19], off offset:1024
	global_load_dwordx4 v[2:5], v[22:23], off
	global_load_dwordx4 v[10:13], v[22:23], off offset:1024
	global_load_dwordx4 v[26:29], v[18:19], off offset:2048
	global_load_dwordx4 v[30:33], v[18:19], off offset:3072
	s_nop 0
	global_load_dwordx4 v[18:21], v[22:23], off offset:2048
	s_nop 0
	global_load_dwordx4 v[22:25], v[22:23], off offset:3072
	s_branch .LBB0_857
